# attention inner loop restructured (c4-outer PV with exp interleave, 4-deep LDS ring) + scan chain: o-wave unused operand loads masked; on top of PEER head-rank rewrite
# speedup vs baseline: 1.0173x; 1.0173x over previous
; DI void phase3_prompt(const P& p, char* smem, int id) {
;   const int tid = threadIdx.x, lane = tid & 63, w = __builtin_amdgcn_readfirstlane(tid >> 6);
;   const int x = id & 7, sl = (id >> 3) & 7, hi = id >> 6;
;   const int bh = hi * 8 + x, b = bh >> 3, h = bh & 7, e0 = sl * 16;
;   const u16* NEGWU = (const u16*)(p.out + O_KP);
;   const u16* KDQG = (const u16*)(p.out + O_VP);
;   const u16* INTRA = (const u16*)((const char*)p.out + 67633152);
;   const float* GL = (const float*)(p.ws + WS_GL);
;   u16* OA = (u16*)(p.ws + WS_OA);
;   float* SSQ = (float*)(p.ws + WS_SSQ);
;   u16* Sl = (u16*)smem;
;   u16* Vn = Sl + 16 * 136;
;   float* dec = (float*)(Vn + 16 * 72);
;   u16* Os = (u16*)(dec + 256);
;   __syncthreads();
;   for (int i = tid; i < 16 * 136; i += NT) Sl[i] = 0;
;   if (tid < 256) dec[tid] = GL[(b * 8 + h) * 256 + tid];
;   f32x4 Sreg[2] = {f32x4{0.f, 0.f, 0.f, 0.f}, f32x4{0.f, 0.f, 0.f, 0.f}};
;   bf16x8 identA;
; #pragma unroll
;   for (int j = 0; j < 8; j++) identA[j] = ((lane >> 4) < 2 && 8 * (lane >> 4) + j == (lane & 15)) ? (short)0x3F80 : (short)0;
;   constexpr int NS = 4;
;   ScanOps st[NS];
;   __syncthreads();
;   constexpr int GS = 8;
;   for (int n0 = 0; n0 < 256; n0 += GS) {
; #pragma unroll
;     for (int j = 0; j < NS - 1; j++) scan_load(st[j], NEGWU, KDQG, INTRA, GL, (b * 8 + h) * 256 + n0 + j, w, lane, e0);
.LBB0_373:
	s_or_b64 exec, exec, s[12:13]
	s_bfe_u32 s64, s90, 0x30003
	s_lshr_b32 s68, s67, 6
	s_lshl_b32 s92, s64, 4
	s_lshl_b32 s66, s66, 8
	s_cmpk_gt_u32 s67, 0xff
	s_cselect_b64 s[16:17], -1, 0
	s_bfe_u32 s12, s67, 0x20006
	s_lshl_b32 s65, s12, 4
	s_lshl_b32 s70, s12, 5
	s_cmpk_lt_u32 s67, 0x100
	s_cselect_b64 s[62:63], -1, 0
	v_lshl_or_b32 v200, s12, 11, v219
	s_and_b64 s[12:13], s[62:63], exec
	s_cselect_b32 s12, s70, s65
	v_or_b32_e32 v233, s12, v195
	s_add_u32 s12, s52, s15
	s_addc_u32 s13, s53, 0
	s_lshl_b32 s15, s64, 5
	s_add_u32 s12, s12, s15
	s_addc_u32 s13, s13, 0
	v_mov_b32_e32 v197, v3
	v_lshl_add_u64 v[202:203], s[12:13], 0, v[196:197]
	s_or_b32 s95, s93, 3
	s_lshl_b32 s94, s68, 5
	s_and_b32 s15, s67, 0xc0
	s_lshl_b32 s12, s91, 5
	s_add_u32 s12, s56, s12
	v_lshl_or_b32 v2, s64, 11, v231
	s_addc_u32 s13, s57, 0
	s_lshl_b32 s64, s64, 2
	s_add_u32 s64, s12, s64
	s_addc_u32 s65, s13, 0
	s_add_i32 s12, s14, s66
	s_ashr_i32 s13, s12, 31
	s_lshl_b32 s71, s68, 9
	s_lshl_b64 s[68:69], s[12:13], 15
	v_or_b32_e32 v4, s68, v194
	v_mov_b32_e32 v5, s69
	v_or_b32_e32 v4, s70, v4
	v_lshlrev_b32_e32 v14, 6, v233
	v_lshl_add_u64 v[206:207], v[4:5], 0, v[2:3]
	v_mov_b32_e32 v4, v3
	v_mov_b32_e32 v5, v3
	v_mov_b32_e32 v2, v3
	v_lshlrev_b32_e32 v208, 1, v14
	v_mov_b64_e32 v[16:17], v[4:5]
	v_mov_b64_e32 v[20:21], v[4:5]
	v_lshl_or_b32 v204, s34, 14, v222
	s_lshl_b64 s[66:67], s[12:13], 13
	s_mov_b32 s96, 0
	s_mov_b32 s97, -8
	v_add_u32_e32 v197, s94, v223
	v_add_u32_e32 v234, s71, v225
	v_add_u32_e32 v235, s15, v224
	s_mov_b32 s87, s33
	v_mov_b64_e32 v[14:15], v[2:3]
	v_mov_b64_e32 v[18:19], v[2:3]
	s_waitcnt lgkmcnt(0)
	s_barrier
	s_or_b64 s[100:101], s[62:63], 1
	s_branch .LBB0_375

; DI void scan_load(ScanOps& o, const u16* NEGWU, const u16* KDQG, const u16* INTRA, const float* GL, int item, int w, int lane, int e0) {
;   const bool sw = w < 4;
;   const int wq = w & 3;
;   const u16* pa = sw ? NEGWU + (size_t)item * 16384 : KDQG + (size_t)item * 16384 + 8192;
;   const u16* pb = sw ? KDQG + (size_t)item * 16384 : INTRA + (size_t)item * 4096;
;   const int rowb = sw ? 32 * wq : 16 * wq, dstep = sw ? 16 : 0;
; #pragma unroll
;   for (int kk = 0; kk < 4; kk++) o.a[kk] = ldfrag(pa + (16 * wq + (lane & 15)) * 128 + kk * 32 + (lane >> 4) * 8);
; #pragma unroll
;   for (int dt = 0; dt < 2; dt++)
; #pragma unroll
;     for (int kk = 0; kk < 2; kk++) o.b[dt * 2 + kk] = ldfrag(pb + (rowb + dt * dstep + (lane & 15)) * 64 + kk * 32 + (lane >> 4) * 8);
;   o.ub = ldfrag(NEGWU + (size_t)item * 16384 + 8192 + (e0 + (lane & 15)) * 64 + 16 * wq + 8 * ((lane >> 4) & 1));
; }
; DI void phase3_prompt(const P& p, char* smem, int id) {
;     ...
;     for (int j = 0; j < NS - 1; j++) scan_load(st[j], NEGWU, KDQG, INTRA, GL, (b * 8 + h) * 256 + n0 + j, w, lane, e0);
.LBB0_379:
	v_lshlrev_b32_e32 v2, 1, v200
	v_lshl_add_u64 v[4:5], s[12:13], 0, v[2:3]
	v_mov_b32_e32 v199, v3
	v_lshl_add_u64 v[4:5], v[4:5], 0, v[198:199]
	global_load_dwordx4 v[74:77], v[4:5], off
	global_load_dwordx4 v[78:81], v[4:5], off offset:64
	global_load_dwordx4 v[82:85], v[4:5], off offset:128
	global_load_dwordx4 v[58:61], v[4:5], off offset:192
	v_lshl_add_u64 v[4:5], s[70:71], 0, v[198:199]
	v_mov_b32_e32 v209, v3
	v_lshl_add_u64 v[22:23], v[4:5], 0, v[208:209]
	global_load_dwordx4 v[50:53], v[22:23], off
	global_load_dwordx4 v[26:29], v[22:23], off offset:64
	v_add_lshl_u32 v22, s15, v233, 7
	v_mov_b32_e32 v23, v3
	v_readlane_b32 s36, v251, 1
	v_lshl_add_u64 v[4:5], v[4:5], 0, v[22:23]
	v_readlane_b32 s48, v251, 13
	v_readlane_b32 s49, v251, 14
	s_mov_b64 exec, s[100:101]
	global_load_dwordx4 v[42:45], v[4:5], off
	s_mov_b64 exec, -1
	s_mov_b64 exec, s[100:101]
	global_load_dwordx4 v[38:41], v[4:5], off offset:64
	s_mov_b64 exec, -1
	v_lshl_add_u64 v[4:5], s[48:49], 0, v[206:207]
	v_add_co_u32_e32 v22, vcc, 0x8104000, v4
	s_mov_b64 s[74:75], -1
	s_nop 0
	v_addc_co_u32_e32 v23, vcc, 0, v5, vcc
	s_mov_b64 exec, s[100:101]
	global_load_dwordx4 v[90:93], v[22:23], off
	s_mov_b64 exec, -1
	v_cndmask_b32_e64 v22, 0, 1, s[16:17]
	v_cmp_ne_u32_e64 s[12:13], 1, v22
	s_andn2_b64 vcc, exec, s[16:17]
	v_readlane_b32 s37, v251, 2
	v_readlane_b32 s38, v251, 3
	v_readlane_b32 s39, v251, 4
	v_readlane_b32 s40, v251, 5
	v_readlane_b32 s41, v251, 6
	v_readlane_b32 s42, v251, 7
	v_readlane_b32 s43, v251, 8
	v_readlane_b32 s44, v251, 9
	v_readlane_b32 s45, v251, 10
	v_readlane_b32 s46, v251, 11
	v_readlane_b32 s47, v251, 12
	v_readlane_b32 s50, v251, 15
	v_readlane_b32 s51, v251, 16
	s_cbranch_vccnz .LBB0_381
	v_readlane_b32 s36, v251, 1
	v_readlane_b32 s48, v251, 13
	v_readlane_b32 s49, v251, 14
	s_add_u32 s15, s48, s68
	s_addc_u32 s71, s49, s69
	s_add_u32 s70, s15, 0x1010c000
	s_addc_u32 s71, s71, 0
	s_add_u32 s15, s48, s66
	s_addc_u32 s73, s49, s67
	s_add_u32 s72, s15, 0x4082000
	s_addc_u32 s73, s73, 0
	s_mov_b64 s[74:75], 0
	v_readlane_b32 s37, v251, 2
	v_readlane_b32 s38, v251, 3
	v_readlane_b32 s39, v251, 4
	v_readlane_b32 s40, v251, 5
	v_readlane_b32 s41, v251, 6
	v_readlane_b32 s42, v251, 7
	v_readlane_b32 s43, v251, 8
	v_readlane_b32 s44, v251, 9
	v_readlane_b32 s45, v251, 10
	v_readlane_b32 s46, v251, 11
	v_readlane_b32 s47, v251, 12
	v_readlane_b32 s50, v251, 15
	v_readlane_b32 s51, v251, 16

; DI void scan_load(ScanOps& o, const u16* NEGWU, const u16* KDQG, const u16* INTRA, const float* GL, int item, int w, int lane, int e0) {
;   const bool sw = w < 4;
;   const int wq = w & 3;
;   const u16* pa = sw ? NEGWU + (size_t)item * 16384 : KDQG + (size_t)item * 16384 + 8192;
;   const u16* pb = sw ? KDQG + (size_t)item * 16384 : INTRA + (size_t)item * 4096;
;   const int rowb = sw ? 32 * wq : 16 * wq, dstep = sw ? 16 : 0;
; #pragma unroll
;   for (int kk = 0; kk < 4; kk++) o.a[kk] = ldfrag(pa + (16 * wq + (lane & 15)) * 128 + kk * 32 + (lane >> 4) * 8);
; #pragma unroll
;   for (int dt = 0; dt < 2; dt++)
; #pragma unroll
;     for (int kk = 0; kk < 2; kk++) o.b[dt * 2 + kk] = ldfrag(pb + (rowb + dt * dstep + (lane & 15)) * 64 + kk * 32 + (lane >> 4) * 8);
;   o.ub = ldfrag(NEGWU + (size_t)item * 16384 + 8192 + (e0 + (lane & 15)) * 64 + 16 * wq + 8 * ((lane >> 4) & 1));
; }
; DI void phase3_prompt(const P& p, char* smem, int id) {
;     ...
;     for (int j = 0; j < NS - 1; j++) scan_load(st[j], NEGWU, KDQG, INTRA, GL, (b * 8 + h) * 256 + n0 + j, w, lane, e0);
.LBB0_383:
	v_lshl_add_u64 v[22:23], s[70:71], 0, v[2:3]
	v_mov_b32_e32 v199, v3
	v_lshl_add_u64 v[22:23], v[22:23], 0, v[198:199]
	global_load_dwordx4 v[130:133], v[22:23], off
	global_load_dwordx4 v[134:137], v[22:23], off offset:64
	global_load_dwordx4 v[138:141], v[22:23], off offset:128
	global_load_dwordx4 v[126:129], v[22:23], off offset:192
	v_lshl_add_u64 v[22:23], s[72:73], 0, v[198:199]
	v_mov_b32_e32 v209, v3
	v_lshl_add_u64 v[24:25], v[22:23], 0, v[208:209]
	global_load_dwordx4 v[106:109], v[24:25], off
	global_load_dwordx4 v[94:97], v[24:25], off offset:64
	v_add_lshl_u32 v24, s15, v233, 7
	v_mov_b32_e32 v25, v3
	v_lshl_add_u64 v[22:23], v[22:23], 0, v[24:25]
	s_mov_b64 exec, s[100:101]
	global_load_dwordx4 v[102:105], v[22:23], off
	s_mov_b64 exec, -1
	s_mov_b64 exec, s[100:101]
	global_load_dwordx4 v[98:101], v[22:23], off offset:64
	s_mov_b64 exec, -1
	v_add_co_u32_e32 v22, vcc, 0x810c000, v4
	s_mov_b64 s[74:75], -1
	s_nop 0
	v_addc_co_u32_e32 v23, vcc, 0, v5, vcc
	s_mov_b64 exec, s[100:101]
	global_load_dwordx4 v[158:161], v[22:23], off
	s_mov_b64 exec, -1
	s_and_b64 vcc, exec, s[12:13]
	s_cbranch_vccnz .LBB0_385
	v_readlane_b32 s36, v251, 1
	v_readlane_b32 s48, v251, 13
	v_readlane_b32 s49, v251, 14
	s_add_u32 s15, s48, s68
	s_addc_u32 s71, s49, s69
	s_add_u32 s70, s15, 0x10114000
	s_addc_u32 s71, s71, 0
	s_add_u32 s15, s48, s66
	s_addc_u32 s73, s49, s67
	s_add_u32 s72, s15, 0x4084000
	s_addc_u32 s73, s73, 0
	s_mov_b64 s[74:75], 0
	v_readlane_b32 s37, v251, 2
	v_readlane_b32 s38, v251, 3
	v_readlane_b32 s39, v251, 4
	v_readlane_b32 s40, v251, 5
	v_readlane_b32 s41, v251, 6
	v_readlane_b32 s42, v251, 7
	v_readlane_b32 s43, v251, 8
	v_readlane_b32 s44, v251, 9
	v_readlane_b32 s45, v251, 10
	v_readlane_b32 s46, v251, 11
	v_readlane_b32 s47, v251, 12
	v_readlane_b32 s50, v251, 15
	v_readlane_b32 s51, v251, 16

; DI void scan_load(ScanOps& o, const u16* NEGWU, const u16* KDQG, const u16* INTRA, const float* GL, int item, int w, int lane, int e0) {
;   const bool sw = w < 4;
;   const int wq = w & 3;
;   const u16* pa = sw ? NEGWU + (size_t)item * 16384 : KDQG + (size_t)item * 16384 + 8192;
;   const u16* pb = sw ? KDQG + (size_t)item * 16384 : INTRA + (size_t)item * 4096;
;   const int rowb = sw ? 32 * wq : 16 * wq, dstep = sw ? 16 : 0;
; #pragma unroll
;   for (int kk = 0; kk < 4; kk++) o.a[kk] = ldfrag(pa + (16 * wq + (lane & 15)) * 128 + kk * 32 + (lane >> 4) * 8);
; #pragma unroll
;   for (int dt = 0; dt < 2; dt++)
; #pragma unroll
;     for (int kk = 0; kk < 2; kk++) o.b[dt * 2 + kk] = ldfrag(pb + (rowb + dt * dstep + (lane & 15)) * 64 + kk * 32 + (lane >> 4) * 8);
;   o.ub = ldfrag(NEGWU + (size_t)item * 16384 + 8192 + (e0 + (lane & 15)) * 64 + 16 * wq + 8 * ((lane >> 4) & 1));
; }
; DI void phase3_prompt(const P& p, char* smem, int id) {
;     ...
;     for (int j = 0; j < NS - 1; j++) scan_load(st[j], NEGWU, KDQG, INTRA, GL, (b * 8 + h) * 256 + n0 + j, w, lane, e0);
.LBB0_387:
	v_lshl_add_u64 v[22:23], s[70:71], 0, v[2:3]
	v_mov_b32_e32 v199, v3
	v_lshl_add_u64 v[22:23], v[22:23], 0, v[198:199]
	global_load_dwordx4 v[146:149], v[22:23], off
	global_load_dwordx4 v[150:153], v[22:23], off offset:64
	global_load_dwordx4 v[154:157], v[22:23], off offset:128
	global_load_dwordx4 v[142:145], v[22:23], off offset:192
	v_lshl_add_u64 v[22:23], s[72:73], 0, v[198:199]
	v_mov_b32_e32 v209, v3
	v_lshl_add_u64 v[24:25], v[22:23], 0, v[208:209]
	global_load_dwordx4 v[122:125], v[24:25], off
	global_load_dwordx4 v[110:113], v[24:25], off offset:64
	v_add_lshl_u32 v24, s15, v233, 7
	v_mov_b32_e32 v25, v3
	v_lshl_add_u64 v[22:23], v[22:23], 0, v[24:25]
	s_mov_b64 exec, s[100:101]
	global_load_dwordx4 v[118:121], v[22:23], off
	s_mov_b64 exec, -1
	s_mov_b64 exec, s[100:101]
	global_load_dwordx4 v[114:117], v[22:23], off offset:64
	s_mov_b64 exec, -1
	v_add_co_u32_e32 v22, vcc, 0x8114000, v4
	s_nop 1
	v_addc_co_u32_e32 v23, vcc, 0, v5, vcc
	s_mov_b64 exec, s[100:101]
	global_load_dwordx4 v[162:165], v[22:23], off
	s_mov_b64 exec, -1
	s_mov_b64 s[72:73], -1
	s_and_b64 vcc, exec, s[16:17]
	s_cbranch_vccz .LBB0_389
	v_readlane_b32 s36, v251, 1
	v_readlane_b32 s48, v251, 13
	v_readlane_b32 s49, v251, 14
	s_add_u32 s14, s48, s68
	s_addc_u32 s15, s49, s69
	s_add_u32 s14, s14, 0x1011c000
	s_addc_u32 s15, s15, 0
	s_add_u32 s70, s48, s66
	s_addc_u32 s71, s49, s67
	s_add_u32 s70, s70, 0x4086000
	v_readlane_b32 s37, v251, 2
	v_readlane_b32 s38, v251, 3
	v_readlane_b32 s39, v251, 4
	v_readlane_b32 s40, v251, 5
	v_readlane_b32 s41, v251, 6
	v_readlane_b32 s42, v251, 7
	v_readlane_b32 s43, v251, 8
	v_readlane_b32 s44, v251, 9
	v_readlane_b32 s45, v251, 10
	v_readlane_b32 s46, v251, 11
	v_readlane_b32 s47, v251, 12
	v_readlane_b32 s50, v251, 15
	v_readlane_b32 s51, v251, 16
	s_addc_u32 s71, s71, 0
	s_mov_b64 s[72:73], 0

; DI f32x4 mfma16(bf16x8 a, bf16x8 b, f32x4 c) { return __builtin_amdgcn_mfma_f32_16x16x32_bf16(a, b, c, 0, 0, 0); }
; DI void scan_load(ScanOps& o, const u16* NEGWU, const u16* KDQG, const u16* INTRA, const float* GL, int item, int w, int lane, int e0) {
;   const bool sw = w < 4;
;   const int wq = w & 3;
;   const u16* pa = sw ? NEGWU + (size_t)item * 16384 : KDQG + (size_t)item * 16384 + 8192;
;   const u16* pb = sw ? KDQG + (size_t)item * 16384 : INTRA + (size_t)item * 4096;
;   const int rowb = sw ? 32 * wq : 16 * wq, dstep = sw ? 16 : 0;
; #pragma unroll
;   for (int kk = 0; kk < 4; kk++) o.a[kk] = ldfrag(pa + (16 * wq + (lane & 15)) * 128 + kk * 32 + (lane >> 4) * 8);
; #pragma unroll
;   for (int dt = 0; dt < 2; dt++)
; #pragma unroll
;     for (int kk = 0; kk < 2; kk++) o.b[dt * 2 + kk] = ldfrag(pb + (rowb + dt * dstep + (lane & 15)) * 64 + kk * 32 + (lane >> 4) * 8);
;   o.ub = ldfrag(NEGWU + (size_t)item * 16384 + 8192 + (e0 + (lane & 15)) * 64 + 16 * wq + 8 * ((lane >> 4) & 1));
; }
; DI void phase3_prompt(const P& p, char* smem, int id) {
;     ...
;       if (j + NS - 1 < GS) scan_load(st[(j + NS - 1) % NS], NEGWU, KDQG, INTRA, GL, (b * 8 + h) * 256 + n + NS - 1, w, lane, e0);
;       __builtin_amdgcn_sched_barrier(0);
;       const ScanOps& cur = st[j % NS];
;       bf16x8 sf[4];
; #pragma unroll
;       for (int kk = 0; kk < 4; kk++) sf[kk] = ldfrag(Sl + (lane & 15) * 136 + kk * 32 + (lane >> 4) * 8);
;       f32x4 acc = f32x4{0.f, 0.f, 0.f, 0.f};
;       if (w < 4) acc = mfma16(identA, cur.ub, acc);
.LBB0_391:
	v_lshl_add_u64 v[22:23], s[14:15], 0, v[2:3]
	v_mov_b32_e32 v199, v3
	v_lshl_add_u64 v[22:23], v[22:23], 0, v[198:199]
	global_load_dwordx4 v[62:65], v[22:23], off
	global_load_dwordx4 v[66:69], v[22:23], off offset:64
	global_load_dwordx4 v[70:73], v[22:23], off offset:128
	global_load_dwordx4 v[54:57], v[22:23], off offset:192
	s_waitcnt vmcnt(36)
	v_lshl_add_u64 v[30:31], s[70:71], 0, v[198:199]
	v_mov_b32_e32 v209, v3
	v_add_lshl_u32 v32, s72, v233, 7
	v_mov_b32_e32 v33, v3
	s_waitcnt vmcnt(35)
	v_add_co_u32_e32 v86, vcc, 0x811c000, v4
	v_lshl_add_u64 v[22:23], v[30:31], 0, v[208:209]
	v_lshl_add_u64 v[30:31], v[30:31], 0, v[32:33]
	v_addc_co_u32_e32 v87, vcc, 0, v5, vcc
	global_load_dwordx4 v[46:49], v[22:23], off
	s_nop 0
	global_load_dwordx4 v[22:25], v[22:23], off offset:64
	s_nop 0
	s_mov_b64 exec, s[100:101]
	global_load_dwordx4 v[34:37], v[30:31], off
	s_mov_b64 exec, -1
	s_nop 0
	s_mov_b64 exec, s[100:101]
	global_load_dwordx4 v[30:33], v[30:31], off offset:64
	s_mov_b64 exec, -1
	s_nop 0
	s_mov_b64 exec, s[100:101]
	global_load_dwordx4 v[86:89], v[86:87], off
	s_mov_b64 exec, -1
	ds_read_b128 v[170:173], v220
	ds_read_b128 v[174:177], v220 offset:64
	ds_read_b128 v[178:181], v220 offset:128
	ds_read_b128 v[166:169], v220 offset:192
	v_cndmask_b32_e64 v183, 0, 1, s[62:63]
	v_mov_b32_e32 v182, 0
	v_cmp_ne_u32_e64 s[14:15], 1, v183
	s_andn2_b64 vcc, exec, s[62:63]
	v_mov_b32_e32 v183, 0
	v_mov_b32_e32 v184, 0
	v_mov_b32_e32 v185, 0
	s_cbranch_vccnz .LBB0_393
	s_waitcnt vmcnt(27)
	v_mfma_f32_16x16x32_bf16 v[182:185], v[6:9], v[90:93], 0

; DI f32x4 mfma16(bf16x8 a, bf16x8 b, f32x4 c) { return __builtin_amdgcn_mfma_f32_16x16x32_bf16(a, b, c, 0, 0, 0); }
; DI void scan_load(ScanOps& o, const u16* NEGWU, const u16* KDQG, const u16* INTRA, const float* GL, int item, int w, int lane, int e0) {
;   const bool sw = w < 4;
;   const int wq = w & 3;
;   const u16* pa = sw ? NEGWU + (size_t)item * 16384 : KDQG + (size_t)item * 16384 + 8192;
;   const u16* pb = sw ? KDQG + (size_t)item * 16384 : INTRA + (size_t)item * 4096;
;   const int rowb = sw ? 32 * wq : 16 * wq, dstep = sw ? 16 : 0;
; #pragma unroll
;   for (int kk = 0; kk < 4; kk++) o.a[kk] = ldfrag(pa + (16 * wq + (lane & 15)) * 128 + kk * 32 + (lane >> 4) * 8);
; #pragma unroll
;   for (int dt = 0; dt < 2; dt++)
; #pragma unroll
;     for (int kk = 0; kk < 2; kk++) o.b[dt * 2 + kk] = ldfrag(pb + (rowb + dt * dstep + (lane & 15)) * 64 + kk * 32 + (lane >> 4) * 8);
;   o.ub = ldfrag(NEGWU + (size_t)item * 16384 + 8192 + (e0 + (lane & 15)) * 64 + 16 * wq + 8 * ((lane >> 4) & 1));
; }
; DI void phase3_prompt(const P& p, char* smem, int id) {
;     ...
;       if (j + NS - 1 < GS) scan_load(st[(j + NS - 1) % NS], NEGWU, KDQG, INTRA, GL, (b * 8 + h) * 256 + n + NS - 1, w, lane, e0);
;       __builtin_amdgcn_sched_barrier(0);
;       const ScanOps& cur = st[j % NS];
;       bf16x8 sf[4];
; #pragma unroll
;       for (int kk = 0; kk < 4; kk++) sf[kk] = ldfrag(Sl + (lane & 15) * 136 + kk * 32 + (lane >> 4) * 8);
;       f32x4 acc = f32x4{0.f, 0.f, 0.f, 0.f};
;       if (w < 4) acc = mfma16(identA, cur.ub, acc);
.LBB0_405:
	v_lshl_add_u64 v[26:27], s[70:71], 0, v[2:3]
	v_mov_b32_e32 v199, v3
	v_lshl_add_u64 v[26:27], v[26:27], 0, v[198:199]
	global_load_dwordx4 v[74:77], v[26:27], off
	global_load_dwordx4 v[78:81], v[26:27], off offset:64
	global_load_dwordx4 v[82:85], v[26:27], off offset:128
	global_load_dwordx4 v[58:61], v[26:27], off offset:192
	s_waitcnt vmcnt(33)
	v_lshl_add_u64 v[38:39], s[72:73], 0, v[198:199]
	v_mov_b32_e32 v209, v3
	v_add_lshl_u32 v40, s74, v233, 7
	v_mov_b32_e32 v41, v3
	s_waitcnt vmcnt(32)
	v_add_co_u32_e32 v90, vcc, 0x8124000, v4
	v_lshl_add_u64 v[26:27], v[38:39], 0, v[208:209]
	v_lshl_add_u64 v[38:39], v[38:39], 0, v[40:41]
	v_addc_co_u32_e32 v91, vcc, 0, v5, vcc
	global_load_dwordx4 v[50:53], v[26:27], off
	s_nop 0
	global_load_dwordx4 v[26:29], v[26:27], off offset:64
	s_nop 0
	s_mov_b64 exec, s[100:101]
	global_load_dwordx4 v[42:45], v[38:39], off
	s_mov_b64 exec, -1
	s_nop 0
	s_mov_b64 exec, s[100:101]
	global_load_dwordx4 v[38:41], v[38:39], off offset:64
	s_mov_b64 exec, -1
	s_nop 0
	s_mov_b64 exec, s[100:101]
	global_load_dwordx4 v[90:93], v[90:91], off
	s_mov_b64 exec, -1
	ds_read_b128 v[170:173], v220
	ds_read_b128 v[174:177], v220 offset:64
	ds_read_b128 v[178:181], v220 offset:128
	ds_read_b128 v[166:169], v220 offset:192
	v_mov_b32_e32 v182, 0
	s_and_b64 vcc, exec, s[14:15]
	v_mov_b32_e32 v183, 0
	v_mov_b32_e32 v184, 0
	v_mov_b32_e32 v185, 0
	s_cbranch_vccnz .LBB0_407
	s_waitcnt vmcnt(28)
	v_mfma_f32_16x16x32_bf16 v[182:185], v[6:9], v[158:161], 0

; DI f32x4 mfma16(bf16x8 a, bf16x8 b, f32x4 c) { return __builtin_amdgcn_mfma_f32_16x16x32_bf16(a, b, c, 0, 0, 0); }
; DI void scan_load(ScanOps& o, const u16* NEGWU, const u16* KDQG, const u16* INTRA, const float* GL, int item, int w, int lane, int e0) {
;   const bool sw = w < 4;
;   const int wq = w & 3;
;   const u16* pa = sw ? NEGWU + (size_t)item * 16384 : KDQG + (size_t)item * 16384 + 8192;
;   const u16* pb = sw ? KDQG + (size_t)item * 16384 : INTRA + (size_t)item * 4096;
;   const int rowb = sw ? 32 * wq : 16 * wq, dstep = sw ? 16 : 0;
; #pragma unroll
;   for (int kk = 0; kk < 4; kk++) o.a[kk] = ldfrag(pa + (16 * wq + (lane & 15)) * 128 + kk * 32 + (lane >> 4) * 8);
; #pragma unroll
;   for (int dt = 0; dt < 2; dt++)
; #pragma unroll
;     for (int kk = 0; kk < 2; kk++) o.b[dt * 2 + kk] = ldfrag(pb + (rowb + dt * dstep + (lane & 15)) * 64 + kk * 32 + (lane >> 4) * 8);
;   o.ub = ldfrag(NEGWU + (size_t)item * 16384 + 8192 + (e0 + (lane & 15)) * 64 + 16 * wq + 8 * ((lane >> 4) & 1));
; }
; DI void phase3_prompt(const P& p, char* smem, int id) {
;     ...
;       if (j + NS - 1 < GS) scan_load(st[(j + NS - 1) % NS], NEGWU, KDQG, INTRA, GL, (b * 8 + h) * 256 + n + NS - 1, w, lane, e0);
;       __builtin_amdgcn_sched_barrier(0);
;       const ScanOps& cur = st[j % NS];
;       bf16x8 sf[4];
; #pragma unroll
;       for (int kk = 0; kk < 4; kk++) sf[kk] = ldfrag(Sl + (lane & 15) * 136 + kk * 32 + (lane >> 4) * 8);
;       f32x4 acc = f32x4{0.f, 0.f, 0.f, 0.f};
;       if (w < 4) acc = mfma16(identA, cur.ub, acc);
.LBB0_419:
	v_lshl_add_u64 v[94:95], s[70:71], 0, v[2:3]
	v_mov_b32_e32 v199, v3
	v_lshl_add_u64 v[94:95], v[94:95], 0, v[198:199]
	global_load_dwordx4 v[130:133], v[94:95], off
	global_load_dwordx4 v[134:137], v[94:95], off offset:64
	global_load_dwordx4 v[138:141], v[94:95], off offset:128
	global_load_dwordx4 v[126:129], v[94:95], off offset:192
	v_lshl_add_u64 v[98:99], s[72:73], 0, v[198:199]
	v_mov_b32_e32 v209, v3
	v_add_lshl_u32 v100, s74, v233, 7
	v_mov_b32_e32 v101, v3
	s_waitcnt vmcnt(33)
	v_add_co_u32_e32 v158, vcc, 0x812c000, v4
	v_lshl_add_u64 v[94:95], v[98:99], 0, v[208:209]
	v_lshl_add_u64 v[98:99], v[98:99], 0, v[100:101]
	v_addc_co_u32_e32 v159, vcc, 0, v5, vcc
	global_load_dwordx4 v[106:109], v[94:95], off
	s_nop 0
	global_load_dwordx4 v[94:97], v[94:95], off offset:64
	s_nop 0
	s_mov_b64 exec, s[100:101]
	global_load_dwordx4 v[102:105], v[98:99], off
	s_mov_b64 exec, -1
	s_nop 0
	s_mov_b64 exec, s[100:101]
	global_load_dwordx4 v[98:101], v[98:99], off offset:64
	s_mov_b64 exec, -1
	s_nop 0
	s_mov_b64 exec, s[100:101]
	global_load_dwordx4 v[158:161], v[158:159], off
	s_mov_b64 exec, -1
	ds_read_b128 v[170:173], v220
	ds_read_b128 v[174:177], v220 offset:64
	ds_read_b128 v[178:181], v220 offset:128
	ds_read_b128 v[166:169], v220 offset:192
	v_mov_b32_e32 v182, 0
	s_and_b64 vcc, exec, s[14:15]
	v_mov_b32_e32 v183, 0
	v_mov_b32_e32 v184, 0
	v_mov_b32_e32 v185, 0
	s_cbranch_vccnz .LBB0_421
	s_waitcnt vmcnt(29)
	v_mfma_f32_16x16x32_bf16 v[182:185], v[6:9], v[162:165], 0

; DI f32x4 mfma16(bf16x8 a, bf16x8 b, f32x4 c) { return __builtin_amdgcn_mfma_f32_16x16x32_bf16(a, b, c, 0, 0, 0); }
; DI void scan_load(ScanOps& o, const u16* NEGWU, const u16* KDQG, const u16* INTRA, const float* GL, int item, int w, int lane, int e0) {
;   const bool sw = w < 4;
;   const int wq = w & 3;
;   const u16* pa = sw ? NEGWU + (size_t)item * 16384 : KDQG + (size_t)item * 16384 + 8192;
;   const u16* pb = sw ? KDQG + (size_t)item * 16384 : INTRA + (size_t)item * 4096;
;   const int rowb = sw ? 32 * wq : 16 * wq, dstep = sw ? 16 : 0;
; #pragma unroll
;   for (int kk = 0; kk < 4; kk++) o.a[kk] = ldfrag(pa + (16 * wq + (lane & 15)) * 128 + kk * 32 + (lane >> 4) * 8);
; #pragma unroll
;   for (int dt = 0; dt < 2; dt++)
; #pragma unroll
;     for (int kk = 0; kk < 2; kk++) o.b[dt * 2 + kk] = ldfrag(pb + (rowb + dt * dstep + (lane & 15)) * 64 + kk * 32 + (lane >> 4) * 8);
;   o.ub = ldfrag(NEGWU + (size_t)item * 16384 + 8192 + (e0 + (lane & 15)) * 64 + 16 * wq + 8 * ((lane >> 4) & 1));
; }
; DI void phase3_prompt(const P& p, char* smem, int id) {
;     ...
;       if (j + NS - 1 < GS) scan_load(st[(j + NS - 1) % NS], NEGWU, KDQG, INTRA, GL, (b * 8 + h) * 256 + n + NS - 1, w, lane, e0);
;       __builtin_amdgcn_sched_barrier(0);
;       const ScanOps& cur = st[j % NS];
;       bf16x8 sf[4];
; #pragma unroll
;       for (int kk = 0; kk < 4; kk++) sf[kk] = ldfrag(Sl + (lane & 15) * 136 + kk * 32 + (lane >> 4) * 8);
;       f32x4 acc = f32x4{0.f, 0.f, 0.f, 0.f};
;       if (w < 4) acc = mfma16(identA, cur.ub, acc);
.LBB0_433:
	v_lshl_add_u64 v[110:111], s[70:71], 0, v[2:3]
	v_mov_b32_e32 v199, v3
	v_lshl_add_u64 v[110:111], v[110:111], 0, v[198:199]
	global_load_dwordx4 v[146:149], v[110:111], off
	global_load_dwordx4 v[150:153], v[110:111], off offset:64
	global_load_dwordx4 v[154:157], v[110:111], off offset:128
	global_load_dwordx4 v[142:145], v[110:111], off offset:192
	v_lshl_add_u64 v[114:115], s[72:73], 0, v[198:199]
	v_mov_b32_e32 v209, v3
	v_add_lshl_u32 v116, s74, v233, 7
	v_mov_b32_e32 v117, v3
	s_waitcnt vmcnt(34)
	v_add_co_u32_e32 v162, vcc, 0x8134000, v4
	v_lshl_add_u64 v[110:111], v[114:115], 0, v[208:209]
	v_lshl_add_u64 v[114:115], v[114:115], 0, v[116:117]
	v_addc_co_u32_e32 v163, vcc, 0, v5, vcc
	global_load_dwordx4 v[122:125], v[110:111], off
	s_nop 0
	global_load_dwordx4 v[110:113], v[110:111], off offset:64
	s_nop 0
	s_mov_b64 exec, s[100:101]
	global_load_dwordx4 v[118:121], v[114:115], off
	s_mov_b64 exec, -1
	s_nop 0
	s_mov_b64 exec, s[100:101]
	global_load_dwordx4 v[114:117], v[114:115], off offset:64
	s_mov_b64 exec, -1
	s_nop 0
	s_mov_b64 exec, s[100:101]
	global_load_dwordx4 v[162:165], v[162:163], off
	s_mov_b64 exec, -1
	ds_read_b128 v[170:173], v220
	ds_read_b128 v[174:177], v220 offset:64
	ds_read_b128 v[178:181], v220 offset:128
	ds_read_b128 v[166:169], v220 offset:192
	v_mov_b32_e32 v182, 0
	s_and_b64 vcc, exec, s[14:15]
	v_mov_b32_e32 v183, 0
	v_mov_b32_e32 v184, 0
	v_mov_b32_e32 v185, 0
	s_cbranch_vccnz .LBB0_435
	s_waitcnt vmcnt(30)
	v_mfma_f32_16x16x32_bf16 v[182:185], v[6:9], v[86:89], 0

; DI f32x4 mfma16(bf16x8 a, bf16x8 b, f32x4 c) { return __builtin_amdgcn_mfma_f32_16x16x32_bf16(a, b, c, 0, 0, 0); }
; DI void scan_load(ScanOps& o, const u16* NEGWU, const u16* KDQG, const u16* INTRA, const float* GL, int item, int w, int lane, int e0) {
;   const bool sw = w < 4;
;   const int wq = w & 3;
;   const u16* pa = sw ? NEGWU + (size_t)item * 16384 : KDQG + (size_t)item * 16384 + 8192;
;   const u16* pb = sw ? KDQG + (size_t)item * 16384 : INTRA + (size_t)item * 4096;
;   const int rowb = sw ? 32 * wq : 16 * wq, dstep = sw ? 16 : 0;
; #pragma unroll
;   for (int kk = 0; kk < 4; kk++) o.a[kk] = ldfrag(pa + (16 * wq + (lane & 15)) * 128 + kk * 32 + (lane >> 4) * 8);
; #pragma unroll
;   for (int dt = 0; dt < 2; dt++)
; #pragma unroll
;     for (int kk = 0; kk < 2; kk++) o.b[dt * 2 + kk] = ldfrag(pb + (rowb + dt * dstep + (lane & 15)) * 64 + kk * 32 + (lane >> 4) * 8);
;   o.ub = ldfrag(NEGWU + (size_t)item * 16384 + 8192 + (e0 + (lane & 15)) * 64 + 16 * wq + 8 * ((lane >> 4) & 1));
; }
; DI void phase3_prompt(const P& p, char* smem, int id) {
;     ...
;       if (j + NS - 1 < GS) scan_load(st[(j + NS - 1) % NS], NEGWU, KDQG, INTRA, GL, (b * 8 + h) * 256 + n + NS - 1, w, lane, e0);
;       __builtin_amdgcn_sched_barrier(0);
;       const ScanOps& cur = st[j % NS];
;       bf16x8 sf[4];
; #pragma unroll
;       for (int kk = 0; kk < 4; kk++) sf[kk] = ldfrag(Sl + (lane & 15) * 136 + kk * 32 + (lane >> 4) * 8);
;       f32x4 acc = f32x4{0.f, 0.f, 0.f, 0.f};
;       if (w < 4) acc = mfma16(identA, cur.ub, acc);
.LBB0_447:
	v_lshl_add_u64 v[22:23], s[70:71], 0, v[2:3]
	v_mov_b32_e32 v199, v3
	v_lshl_add_u64 v[22:23], v[22:23], 0, v[198:199]
	global_load_dwordx4 v[62:65], v[22:23], off
	global_load_dwordx4 v[66:69], v[22:23], off offset:64
	global_load_dwordx4 v[70:73], v[22:23], off offset:128
	global_load_dwordx4 v[54:57], v[22:23], off offset:192
	v_lshl_add_u64 v[30:31], s[72:73], 0, v[198:199]
	v_mov_b32_e32 v209, v3
	v_add_lshl_u32 v2, s74, v233, 7
	v_add_co_u32_e32 v4, vcc, 0x813c000, v4
	v_lshl_add_u64 v[22:23], v[30:31], 0, v[208:209]
	v_lshl_add_u64 v[30:31], v[30:31], 0, v[2:3]
	v_addc_co_u32_e32 v5, vcc, 0, v5, vcc
	global_load_dwordx4 v[46:49], v[22:23], off
	s_nop 0
	global_load_dwordx4 v[22:25], v[22:23], off offset:64
	s_nop 0
	s_mov_b64 exec, s[100:101]
	global_load_dwordx4 v[34:37], v[30:31], off
	s_mov_b64 exec, -1
	s_nop 0
	s_mov_b64 exec, s[100:101]
	global_load_dwordx4 v[30:33], v[30:31], off offset:64
	s_mov_b64 exec, -1
	s_nop 0
	s_mov_b64 exec, s[100:101]
	global_load_dwordx4 v[86:89], v[4:5], off
	s_mov_b64 exec, -1
	ds_read_b128 v[170:173], v220
	ds_read_b128 v[174:177], v220 offset:64
	ds_read_b128 v[178:181], v220 offset:128
	ds_read_b128 v[166:169], v220 offset:192
	v_mov_b32_e32 v182, 0
	s_and_b64 vcc, exec, s[14:15]
	v_mov_b32_e32 v183, 0
	v_mov_b32_e32 v184, 0
	v_mov_b32_e32 v185, 0
	s_cbranch_vccnz .LBB0_449
	s_waitcnt vmcnt(30)
	v_mfma_f32_16x16x32_bf16 v[182:185], v[6:9], v[90:93], 0

; DI void attn_prompt(const P& p, char* smem, int bh, int qb, float lam, float M2) {
;     ...
;   f32x16 ot[4];
; #pragma unroll
;   for (int dt = 0; dt < 4; dt++)
; #pragma unroll
;     for (int i = 0; i < 16; i++) ot[dt][i] = 0.f;
;   f32x16 zinit;
; #pragma unroll
;   for (int i = 0; i < 16; i++) zinit[i] = 0.f;
;   float lsum = 0.f;
;   const u16* kbase = Kn + (size_t)(b * SEQ) * 1024 + h * 128;
;   const u16* vbase = Vt + (size_t)(b * 8 + h) * 128 * SEQ;
;   const u16* gsrc[4];
; #pragma unroll
;   for (int ii = 0; ii < 4; ii++) {
;     int r = (w * 4 + ii) * 8 + (lane >> 3), pos = lane & 7, c = pos ^ ((r >> 1) & 7);
;     if (w < 4) { int key = r & 63, m = r >> 6; gsrc[ii] = kbase + (size_t)key * 1024 + m * 64 + c * 8; }
;     else { int dv = r - 128; gsrc[ii] = vbase + (size_t)dv * SEQ + c * 8; }
;   }
;   const size_t gstep = w < 4 ? (size_t)64 * 1024 : (size_t)64;
;   auto glds = [&](int kt, int bufi) {
;     char* dst = smem + bufi * TILEB + w * 4096;
; #pragma unroll
;     for (int ii = 0; ii < 4; ii++)
;       __builtin_amdgcn_global_load_lds((const unsigned*)(gsrc[ii] + (size_t)kt * gstep), (unsigned*)(dst + ii * 1024), 16, 0, 0);
;   };
;   const int swz16 = ((l31 >> 1) & 7) << 4;
;   const int krow = (map * 64 + l31) * 128, vrow = (128 + l31) * 128;
;   __syncthreads();
;   asm volatile("s_waitcnt vmcnt(0)" ::: "memory");
;   glds(0, 0);
;   glds(1, 1);
.LBB0_770:
	s_lshl_b32 s1, s51, 12
	v_mov_b32_e32 v141, v3
	s_add_i32 s30, s1, 0
	v_mov_b32_e32 v143, v3
	v_lshl_add_u64 v[156:157], v[4:5], 0, v[140:141]
	s_barrier
	s_waitcnt vmcnt(0)
	s_mov_b32 m0, s30
	v_lshl_add_u64 v[154:155], v[6:7], 0, v[142:143]
	global_load_lds_dwordx4 v[156:157], off
	s_add_i32 m0, s30, 0x400
	v_lshl_add_u64 v[152:153], v[10:11], 0, v[140:141]
	v_mov_b32_e32 v145, v3
	global_load_lds_dwordx4 v[154:155], off
	s_add_i32 m0, s30, 0x800
	v_lshl_add_u64 v[158:159], v[8:9], 0, v[144:145]
	global_load_lds_dwordx4 v[152:153], off
	s_add_i32 m0, s30, 0xc00
	s_lshl_b32 s28, s28, 1
	s_mov_b32 s29, s5
	global_load_lds_dwordx4 v[158:159], off
	s_add_i32 m0, s30, 0x8000
	v_lshl_add_u64 v[4:5], v[156:157], 0, s[28:29]
	global_load_lds_dwordx4 v[4:5], off
	v_lshl_add_u64 v[4:5], v[154:155], 0, s[28:29]
	s_add_i32 m0, s30, 0x8400
	s_lshl_b32 s34, s49, 1
	global_load_lds_dwordx4 v[4:5], off
	v_lshl_add_u64 v[4:5], v[152:153], 0, s[28:29]
	s_add_i32 m0, s30, 0x8800
	v_mov_b32_e32 v16, v3
	global_load_lds_dwordx4 v[4:5], off
	v_lshl_add_u64 v[4:5], v[158:159], 0, s[28:29]
	s_add_i32 m0, s30, 0x8c00
	s_lshl_b64 s[52:53], s[28:29], 1
	global_load_lds_dwordx4 v[4:5], off
	v_lshl_add_u64 v[4:5], v[156:157], 0, s[52:53]
	s_add_i32 m0, s30, 0x10000
	s_nop 0
	global_load_lds_dwordx4 v[4:5], off
	v_lshl_add_u64 v[4:5], v[154:155], 0, s[52:53]
	s_add_i32 m0, s30, 0x10400
	s_nop 0
	global_load_lds_dwordx4 v[4:5], off
	v_lshl_add_u64 v[4:5], v[152:153], 0, s[52:53]
	s_add_i32 m0, s30, 0x10800
	s_nop 0
	global_load_lds_dwordx4 v[4:5], off
	v_lshl_add_u64 v[4:5], v[158:159], 0, s[52:53]
	s_add_i32 m0, s30, 0x10c00
	s_lshr_b32 s28, s50, 8
	global_load_lds_dwordx4 v[4:5], off
	v_mov_b32_e32 v17, v3
	s_add_i32 s31, s28, s34
	s_lshl_b32 s30, s48, 13
	v_mov_b32_e32 v2, v3
	v_mov_b32_e32 v4, v3
	v_mov_b32_e32 v5, v3
	v_mov_b32_e32 v6, v3
	v_mov_b32_e32 v7, v3
	v_mov_b32_e32 v8, v3
	v_mov_b32_e32 v9, v3
	v_mov_b32_e32 v10, v3
	v_mov_b32_e32 v11, v3
	v_mov_b32_e32 v12, v3
	v_mov_b32_e32 v13, v3
	v_mov_b32_e32 v14, v3
	v_mov_b32_e32 v15, v3
	v_mov_b64_e32 v[32:33], v[16:17]
	v_mov_b64_e32 v[48:49], v[16:17]
	v_mov_b64_e32 v[64:65], v[16:17]
	v_mov_b64_e32 v[80:81], v[16:17]
	s_add_i32 s31, s31, 1
	s_or_b32 s35, s34, 1
	s_mov_b32 s49, 0
	v_or_b32_e32 v139, s30, v184
	v_or_b32_e32 v141, s30, v185
	v_or_b32_e32 v143, s30, v188
	v_or_b32_e32 v145, s30, v189
	v_mov_b32_e32 v147, 0
	s_mov_b64 s[28:29], 0
	s_mov_b32 s50, 2
	v_mov_b64_e32 v[30:31], v[14:15]
	v_mov_b64_e32 v[28:29], v[12:13]
	v_mov_b64_e32 v[26:27], v[10:11]
	v_mov_b64_e32 v[24:25], v[8:9]
	v_mov_b64_e32 v[22:23], v[6:7]
	v_mov_b64_e32 v[20:21], v[4:5]
	v_mov_b64_e32 v[18:19], v[2:3]
	v_mov_b64_e32 v[46:47], v[14:15]
	v_mov_b64_e32 v[44:45], v[12:13]
	v_mov_b64_e32 v[42:43], v[10:11]
	v_mov_b64_e32 v[40:41], v[8:9]
	v_mov_b64_e32 v[38:39], v[6:7]
	v_mov_b64_e32 v[36:37], v[4:5]
	v_mov_b64_e32 v[34:35], v[2:3]
	v_mov_b64_e32 v[62:63], v[14:15]
	v_mov_b64_e32 v[60:61], v[12:13]
	v_mov_b64_e32 v[58:59], v[10:11]
	v_mov_b64_e32 v[56:57], v[8:9]
	v_mov_b64_e32 v[54:55], v[6:7]
	v_mov_b64_e32 v[52:53], v[4:5]
	v_mov_b64_e32 v[50:51], v[2:3]
	v_mov_b64_e32 v[78:79], v[14:15]
	v_mov_b64_e32 v[76:77], v[12:13]
	v_mov_b64_e32 v[74:75], v[10:11]
	v_mov_b64_e32 v[72:73], v[8:9]
	v_mov_b64_e32 v[70:71], v[6:7]
	v_mov_b64_e32 v[68:69], v[4:5]
	v_mov_b64_e32 v[66:67], v[2:3]
	s_branch .LBB0_772

; #define RAW_BARRIER() do { asm volatile("s_waitcnt lgkmcnt(0)" ::: "memory"); __builtin_amdgcn_s_barrier(); } while (0)
; DI void attn_prompt(const P& p, char* smem, int bh, int qb, float lam, float M2) {
;     ...
;   for (int kt = 0; kt < ntile; kt++) {
;     if (kt + 1 < ntile) asm volatile("s_waitcnt vmcnt(4)" ::: "memory");
;     else asm volatile("s_waitcnt vmcnt(0)" ::: "memory");
;     RAW_BARRIER();
.LBB0_772:
	s_cmp_ge_u32 s28, s34
	s_cbranch_scc1 .Lattn_w4
	s_waitcnt vmcnt(8)
	s_branch .Lattn_wd

; DI void attn_prompt(const P& p, char* smem, int bh, int qb, float lam, float M2) {
;     ...
;   for (int kt = 0; kt < ntile; kt++) {
;     if (kt + 1 < ntile) asm volatile("s_waitcnt vmcnt(4)" ::: "memory");
;     else asm volatile("s_waitcnt vmcnt(0)" ::: "memory");
;     RAW_BARRIER();
;     if (kt + 2 < ntile) glds(kt + 2, (kt + 2) % 3);
;     if (kt < my_nt) {
;       const char* buf = smem + (kt % 3) * TILEB;
;       bf16x8 kf[2][4];
; #pragma unroll
;       for (int tk = 0; tk < 2; tk++)
; #pragma unroll
;         for (int kk = 0; kk < 4; kk++) kf[tk][kk] = *(const bf16x8*)(buf + krow + tk * 4096 + (((kk * 2 + hf) << 4) ^ swz16));
;       __builtin_amdgcn_sched_barrier(0);
;       f32x16 st[2];
; #pragma unroll
;       for (int kk = 0; kk < 4; kk++)
; #pragma unroll
;         for (int tk = 0; tk < 2; tk++) st[tk] = mfma32(kf[tk][kk], qf[kk], kk == 0 ? zinit : st[tk]);
;       __builtin_amdgcn_sched_barrier(0);
;       bf16x8 vf0[4], vf1[4];
; #pragma unroll
;       for (int c4 = 0; c4 < 4; c4++) vf0[c4] = *(const bf16x8*)(buf + vrow + 0 * 4096 + (((c4 * 2 + hf) << 4) ^ swz16));
;       __builtin_amdgcn_sched_barrier(0);
;       bf16x8 pf[4];
; #pragma unroll
;       for (int tk = 0; tk < 2; tk++) {
;         float pe[16];
; #pragma unroll
;         for (int i = 0; i < 16; i++) { pe[i] = __builtin_amdgcn_exp2f(st[tk][i]); lsum += pe[i]; }
; #pragma unroll
;         for (int s2 = 0; s2 < 2; s2++) {
;           u32x4 pk = {pack2(pe[8 * s2], pe[8 * s2 + 1]), pack2(pe[8 * s2 + 2], pe[8 * s2 + 3]), pack2(pe[8 * s2 + 4], pe[8 * s2 + 5]), pack2(pe[8 * s2 + 6], pe[8 * s2 + 7])};
;           pf[tk * 2 + s2] = __builtin_bit_cast(bf16x8, pk);
;         }
;       }
;       __builtin_amdgcn_sched_barrier(0);
; #pragma unroll
;       for (int c4 = 0; c4 < 4; c4++) vf1[c4] = *(const bf16x8*)(buf + vrow + 1 * 4096 + (((c4 * 2 + hf) << 4) ^ swz16));
;       __builtin_amdgcn_sched_barrier(0);
; #pragma unroll
;       for (int c4 = 0; c4 < 4; c4++) ot[0] = mfma32(vf0[c4], pf[c4], ot[0]);
;       __builtin_amdgcn_sched_barrier(0);
; #pragma unroll
;       for (int c4 = 0; c4 < 4; c4++) vf0[c4] = *(const bf16x8*)(buf + vrow + 2 * 4096 + (((c4 * 2 + hf) << 4) ^ swz16));
;       __builtin_amdgcn_sched_barrier(0);
; #pragma unroll
;       for (int c4 = 0; c4 < 4; c4++) ot[1] = mfma32(vf1[c4], pf[c4], ot[1]);
;       __builtin_amdgcn_sched_barrier(0);
; #pragma unroll
.Lattn_wd:
	s_waitcnt lgkmcnt(0)
	s_add_u32 s52, s28, 1
	s_cmp_ge_u32 s52, s34
	s_barrier
	s_cbranch_scc1 .LBB0_774
	s_add_u32 s52, s28, 3
	s_addc_u32 s53, s29, 0
	s_and_b32 s51, s52, 3
	s_lshl_b32 s51, s51, 15
	s_add_i32 s51, s51, s1
	s_mov_b32 m0, s51
	s_lshl_b64 s[52:53], s[52:53], s0
	s_lshl_b64 s[52:53], s[52:53], 1
	v_lshl_add_u64 v[4:5], v[156:157], 0, s[52:53]
	global_load_lds_dwordx4 v[4:5], off
	v_lshl_add_u64 v[4:5], v[154:155], 0, s[52:53]
	s_add_i32 m0, s51, 0x400
	s_nop 0
	global_load_lds_dwordx4 v[4:5], off
	v_lshl_add_u64 v[4:5], v[152:153], 0, s[52:53]
	s_add_i32 m0, s51, 0x800
	s_nop 0
	global_load_lds_dwordx4 v[4:5], off
	v_lshl_add_u64 v[4:5], v[158:159], 0, s[52:53]
	s_add_i32 m0, s51, 0xc00
	s_nop 0
	global_load_lds_dwordx4 v[4:5], off
.LBB0_774:
	s_cmp_ge_u32 s28, s31
	s_cbranch_scc1 .LBB0_771
	s_and_b32 s51, s28, 3
	s_lshl_b32 s51, s51, 15
	v_add_u32_e32 v16, s51, v200
	v_add_u32_e32 v2, v16, v139
	v_add_u32_e32 v17, v16, v141
	v_add_u32_e32 v215, v16, v143
	v_add_u32_e32 v236, v16, v145
	ds_read_b128 v[4:7], v2
	ds_read_b128 v[8:11], v17
	ds_read_b128 v[12:15], v215
	ds_read_b128 v[216:219], v236
	ds_read_b128 v[220:223], v2 offset:4096
	ds_read_b128 v[224:227], v17 offset:4096
	ds_read_b128 v[228:231], v215 offset:4096
	ds_read_b128 v[232:235], v236 offset:4096
	v_add_u32_e32 v2, v16, v204
	v_add_u32_e32 v17, v16, v203
	v_add_u32_e32 v215, v16, v202
	v_add_u32_e32 v236, v16, v189
	s_waitcnt lgkmcnt(7)
	v_mfma_f32_32x32x16_bf16 v[98:113], v[4:7], v[126:129], 0
	s_waitcnt lgkmcnt(6)
	v_mfma_f32_32x32x16_bf16 v[98:113], v[8:11], v[122:125], v[98:113]
	s_waitcnt lgkmcnt(5)
	v_mfma_f32_32x32x16_bf16 v[98:113], v[12:15], v[118:121], v[98:113]
	s_waitcnt lgkmcnt(4)
	v_mfma_f32_32x32x16_bf16 v[98:113], v[216:219], v[114:117], v[98:113]
	s_waitcnt lgkmcnt(3)
	v_mfma_f32_32x32x16_bf16 v[82:97], v[220:223], v[126:129], 0
	ds_read_b128 v[4:7], v2
	ds_read_b128 v[8:11], v2 offset:4096
	ds_read_b128 v[12:15], v2 offset:8192
	ds_read_b128 v[216:219], v2 offset:12288
	s_waitcnt lgkmcnt(6)
	v_mfma_f32_32x32x16_bf16 v[82:97], v[224:227], v[122:125], v[82:97]
	s_nop 5
	v_exp_f32_e32 v98, v98
	v_exp_f32_e32 v99, v99
	v_exp_f32_e32 v100, v100
	s_waitcnt lgkmcnt(5)
	v_mfma_f32_32x32x16_bf16 v[82:97], v[228:231], v[118:121], v[82:97]
	v_exp_f32_e32 v101, v101
	v_exp_f32_e32 v102, v102
	v_exp_f32_e32 v103, v103
	s_waitcnt lgkmcnt(4)
	v_mfma_f32_32x32x16_bf16 v[82:97], v[232:235], v[114:117], v[82:97]
	v_exp_f32_e32 v104, v104
	v_exp_f32_e32 v105, v105
	v_add_f32_e32 v147, v98, v147
	v_add_f32_e32 v147, v99, v147
	v_add_f32_e32 v147, v100, v147
	v_add_f32_e32 v147, v101, v147
	v_add_f32_e32 v147, v102, v147
	v_add_f32_e32 v147, v103, v147
	v_add_f32_e32 v147, v104, v147
	v_add_f32_e32 v147, v105, v147
	v_cvt_pk_bf16_f32 v98, v98, v99
	v_cvt_pk_bf16_f32 v99, v100, v101
	v_cvt_pk_bf16_f32 v100, v102, v103
	v_cvt_pk_bf16_f32 v101, v104, v105
	ds_read_b128 v[220:223], v17
	ds_read_b128 v[224:227], v17 offset:4096
	ds_read_b128 v[228:231], v17 offset:8192
	ds_read_b128 v[232:235], v17 offset:12288
	s_waitcnt lgkmcnt(7)
	v_mfma_f32_32x32x16_bf16 v[66:81], v[4:7], v[98:101], v[66:81]
	v_exp_f32_e32 v106, v106
	v_exp_f32_e32 v107, v107
	v_exp_f32_e32 v108, v108
	v_exp_f32_e32 v109, v109
	v_exp_f32_e32 v110, v110
	s_waitcnt lgkmcnt(6)
	v_mfma_f32_32x32x16_bf16 v[50:65], v[8:11], v[98:101], v[50:65]
	v_exp_f32_e32 v111, v111
	v_exp_f32_e32 v112, v112
	v_exp_f32_e32 v113, v113
	v_add_f32_e32 v147, v106, v147
	v_add_f32_e32 v147, v107, v147
	s_waitcnt lgkmcnt(5)
	v_mfma_f32_32x32x16_bf16 v[34:49], v[12:15], v[98:101], v[34:49]
	v_add_f32_e32 v147, v108, v147
	v_add_f32_e32 v147, v109, v147
	v_add_f32_e32 v147, v110, v147
	v_add_f32_e32 v147, v111, v147
	v_add_f32_e32 v147, v112, v147
	s_waitcnt lgkmcnt(4)
	v_mfma_f32_32x32x16_bf16 v[18:33], v[216:219], v[98:101], v[18:33]
	v_add_f32_e32 v147, v113, v147
	v_cvt_pk_bf16_f32 v102, v106, v107
	v_cvt_pk_bf16_f32 v103, v108, v109
	v_cvt_pk_bf16_f32 v104, v110, v111
	v_cvt_pk_bf16_f32 v105, v112, v113
	ds_read_b128 v[4:7], v215
	ds_read_b128 v[8:11], v215 offset:4096
	ds_read_b128 v[12:15], v215 offset:8192
	ds_read_b128 v[216:219], v215 offset:12288
	s_waitcnt lgkmcnt(7)
	v_mfma_f32_32x32x16_bf16 v[66:81], v[220:223], v[102:105], v[66:81]
	v_exp_f32_e32 v82, v82
	v_exp_f32_e32 v83, v83
	v_exp_f32_e32 v84, v84
	v_exp_f32_e32 v85, v85
	v_exp_f32_e32 v86, v86
	s_waitcnt lgkmcnt(6)
	v_mfma_f32_32x32x16_bf16 v[50:65], v[224:227], v[102:105], v[50:65]
	v_exp_f32_e32 v87, v87
	v_exp_f32_e32 v88, v88
	v_exp_f32_e32 v89, v89
	v_add_f32_e32 v147, v82, v147
	v_add_f32_e32 v147, v83, v147
	s_waitcnt lgkmcnt(5)
	v_mfma_f32_32x32x16_bf16 v[34:49], v[228:231], v[102:105], v[34:49]
	v_add_f32_e32 v147, v84, v147
	v_add_f32_e32 v147, v85, v147
	v_add_f32_e32 v147, v86, v147
	v_add_f32_e32 v147, v87, v147
	v_add_f32_e32 v147, v88, v147
	s_waitcnt lgkmcnt(4)
	v_mfma_f32_32x32x16_bf16 v[18:33], v[232:235], v[102:105], v[18:33]
	v_add_f32_e32 v147, v89, v147
	v_cvt_pk_bf16_f32 v82, v82, v83
	v_cvt_pk_bf16_f32 v83, v84, v85
	v_cvt_pk_bf16_f32 v84, v86, v87
	v_cvt_pk_bf16_f32 v85, v88, v89
	ds_read_b128 v[220:223], v236 offset:16384
	ds_read_b128 v[224:227], v236 offset:20480
	ds_read_b128 v[228:231], v236 offset:24576
	ds_read_b128 v[232:235], v236 offset:28672
	s_waitcnt lgkmcnt(7)
	v_mfma_f32_32x32x16_bf16 v[66:81], v[4:7], v[82:85], v[66:81]
	v_exp_f32_e32 v90, v90
	v_exp_f32_e32 v91, v91
	v_exp_f32_e32 v92, v92
	v_exp_f32_e32 v93, v93
	v_exp_f32_e32 v94, v94
	s_waitcnt lgkmcnt(6)
	v_mfma_f32_32x32x16_bf16 v[50:65], v[8:11], v[82:85], v[50:65]
	v_exp_f32_e32 v95, v95
	v_exp_f32_e32 v96, v96
	v_exp_f32_e32 v97, v97
	v_add_f32_e32 v147, v90, v147
	v_add_f32_e32 v147, v91, v147
	s_waitcnt lgkmcnt(5)
	v_mfma_f32_32x32x16_bf16 v[34:49], v[12:15], v[82:85], v[34:49]
	v_add_f32_e32 v147, v92, v147
	v_add_f32_e32 v147, v93, v147
	v_add_f32_e32 v147, v94, v147
	v_add_f32_e32 v147, v95, v147
	v_add_f32_e32 v147, v96, v147
	s_waitcnt lgkmcnt(4)
	v_mfma_f32_32x32x16_bf16 v[18:33], v[216:219], v[82:85], v[18:33]
	v_add_f32_e32 v147, v97, v147
	v_cvt_pk_bf16_f32 v86, v90, v91
	v_cvt_pk_bf16_f32 v87, v92, v93
	v_cvt_pk_bf16_f32 v88, v94, v95
	v_cvt_pk_bf16_f32 v89, v96, v97
	s_nop 1
	s_waitcnt lgkmcnt(3)
	v_mfma_f32_32x32x16_bf16 v[66:81], v[220:223], v[86:89], v[66:81]
	s_waitcnt lgkmcnt(2)
	v_mfma_f32_32x32x16_bf16 v[50:65], v[224:227], v[86:89], v[50:65]
	s_waitcnt lgkmcnt(1)
	v_mfma_f32_32x32x16_bf16 v[34:49], v[228:231], v[86:89], v[34:49]
	s_waitcnt lgkmcnt(0)
	v_mfma_f32_32x32x16_bf16 v[18:33], v[232:235], v[86:89], v[18:33]
	s_branch .LBB0_771
; DI void attn_prompt(const P& p, char* smem, int bh, int qb, float lam, float M2) {
;     ...
;   for (int kt = 0; kt < ntile; kt++) {
;     if (kt + 1 < ntile) asm volatile("s_waitcnt vmcnt(4)" ::: "memory");
;     else asm volatile("s_waitcnt vmcnt(0)" ::: "memory");
;     RAW_BARRIER();
;     if (kt + 2 < ntile) glds(kt + 2, (kt + 2) % 3);
;     if (kt < my_nt) {
;       const char* buf = smem + (kt % 3) * TILEB;
;       bf16x8 kf[2][4];
; #pragma unroll
;       for (int tk = 0; tk < 2; tk++)
; #pragma unroll
;         for (int kk = 0; kk < 4; kk++) kf[tk][kk] = *(const bf16x8*)(buf + krow + tk * 4096 + (((kk * 2 + hf) << 4) ^ swz16));
;       __builtin_amdgcn_sched_barrier(0);
;       f32x16 st[2];
; #pragma unroll
;       for (int kk = 0; kk < 4; kk++)
; #pragma unroll
;         for (int tk = 0; tk < 2; tk++) st[tk] = mfma32(kf[tk][kk], qf[kk], kk == 0 ? zinit : st[tk]);
;       __builtin_amdgcn_sched_barrier(0);
;       bf16x8 vf0[4], vf1[4];
; #pragma unroll
;       for (int c4 = 0; c4 < 4; c4++) vf0[c4] = *(const bf16x8*)(buf + vrow + 0 * 4096 + (((c4 * 2 + hf) << 4) ^ swz16));
;       __builtin_amdgcn_sched_barrier(0);
;       bf16x8 pf[4];
; #pragma unroll
;       for (int tk = 0; tk < 2; tk++) {
;         float pe[16];
; #pragma unroll
;         for (int i = 0; i < 16; i++) { pe[i] = __builtin_amdgcn_exp2f(st[tk][i]); lsum += pe[i]; }
; #pragma unroll
;         for (int s2 = 0; s2 < 2; s2++) {
;           u32x4 pk = {pack2(pe[8 * s2], pe[8 * s2 + 1]), pack2(pe[8 * s2 + 2], pe[8 * s2 + 3]), pack2(pe[8 * s2 + 4], pe[8 * s2 + 5]), pack2(pe[8 * s2 + 6], pe[8 * s2 + 7])};
;           pf[tk * 2 + s2] = __builtin_bit_cast(bf16x8, pk);
;         }
;       }
;       __builtin_amdgcn_sched_barrier(0);
; #pragma unroll
;       for (int c4 = 0; c4 < 4; c4++) vf1[c4] = *(const bf16x8*)(buf + vrow + 1 * 4096 + (((c4 * 2 + hf) << 4) ^ swz16));
;       __builtin_amdgcn_sched_barrier(0);
; #pragma unroll
;       for (int c4 = 0; c4 < 4; c4++) ot[0] = mfma32(vf0[c4], pf[c4], ot[0]);
;       __builtin_amdgcn_sched_barrier(0);
; #pragma unroll
;       for (int c4 = 0; c4 < 4; c4++) vf0[c4] = *(const bf16x8*)(buf + vrow + 2 * 4096 + (((c4 * 2 + hf) << 4) ^ swz16));
;       __builtin_amdgcn_sched_barrier(0);
; #pragma unroll
;       for (int c4 = 0; c4 < 4; c4++) ot[1] = mfma32(vf1[c4], pf[c4], ot[1]);
;       __builtin_amdgcn_sched_barrier(0);
; #pragma unroll
.LBB0_776:
	s_waitcnt vmcnt(0)
	s_waitcnt lgkmcnt(0)
	s_cmp_ge_u32 s28, s31
	s_barrier
	s_cbranch_scc1 .LBB0_778
	s_and_b32 s0, s28, 3
	s_lshl_b32 s0, s0, 15
	v_or_b32_e32 v2, s30, v183
	s_add_i32 s0, s0, 0
	v_add_u32_e32 v2, s0, v2
	v_add_u32_e32 v8, v2, v184
	v_add_u32_e32 v16, v2, v185
	v_add_u32_e32 v17, v2, v188
	v_add_u32_e32 v2, v2, v189
	ds_read_b128 v[4:7], v8
	ds_read_b128 v[8:11], v8 offset:4096
	ds_read_b128 v[12:15], v16
	ds_read_b128 v[152:155], v16 offset:4096
	ds_read_b128 v[156:159], v17
	ds_read_b128 v[216:219], v17 offset:4096
	ds_read_b128 v[220:223], v2
	ds_read_b128 v[224:227], v2 offset:4096
	s_waitcnt lgkmcnt(0)
	v_mfma_f32_32x32x16_bf16 v[98:113], v[4:7], v[126:129], 0
	v_mfma_f32_32x32x16_bf16 v[82:97], v[8:11], v[126:129], 0
	v_mfma_f32_32x32x16_bf16 v[98:113], v[12:15], v[122:125], v[98:113]
	v_mfma_f32_32x32x16_bf16 v[82:97], v[152:155], v[122:125], v[82:97]
	v_mfma_f32_32x32x16_bf16 v[98:113], v[156:159], v[118:121], v[98:113]
	v_mfma_f32_32x32x16_bf16 v[82:97], v[216:219], v[118:121], v[82:97]
	v_mfma_f32_32x32x16_bf16 v[98:113], v[220:223], v[114:117], v[98:113]
	v_mfma_f32_32x32x16_bf16 v[82:97], v[224:227], v[114:117], v[82:97]
	v_add_u32_e32 v2, s0, v183
	v_add_u32_e32 v16, v2, v184
	v_add_u32_e32 v118, v2, v188
	v_add_u32_e32 v17, v2, v185
	ds_read_b128 v[4:7], v16 offset:16384
	ds_read_b128 v[8:11], v17 offset:16384
	v_add_u32_e32 v2, v2, v189
	ds_read_b128 v[12:15], v118 offset:16384
	ds_read_b128 v[114:117], v2 offset:16384
	s_nop 1
	v_exp_f32_e32 v119, v98
	v_exp_f32_e32 v120, v99
	v_exp_f32_e32 v121, v100
	v_exp_f32_e32 v122, v101
	v_exp_f32_e32 v123, v102
	v_cvt_pk_bf16_f32 v98, v119, v120
	v_add_f32_e32 v119, v147, v119
	v_exp_f32_e32 v124, v103
	v_add_f32_e32 v119, v120, v119
	v_exp_f32_e32 v125, v104
	v_add_f32_e32 v119, v121, v119
	v_exp_f32_e32 v126, v105
	v_add_f32_e32 v119, v122, v119
	v_exp_f32_e32 v106, v106
	v_exp_f32_e32 v107, v107
	v_add_f32_e32 v119, v123, v119
	v_add_f32_e32 v119, v124, v119
	v_exp_f32_e32 v108, v108
	v_add_f32_e32 v119, v125, v119
	v_exp_f32_e32 v109, v109
	v_add_f32_e32 v119, v126, v119
	v_exp_f32_e32 v110, v110
	v_cvt_pk_bf16_f32 v102, v106, v107
	v_add_f32_e32 v106, v106, v119
	v_exp_f32_e32 v111, v111
	v_add_f32_e32 v106, v107, v106
	v_exp_f32_e32 v112, v112
	v_add_f32_e32 v106, v108, v106
	v_exp_f32_e32 v113, v113
	v_add_f32_e32 v106, v109, v106
	v_add_f32_e32 v106, v110, v106
	v_exp_f32_e32 v107, v82
	v_cvt_pk_bf16_f32 v103, v108, v109
	v_add_f32_e32 v106, v111, v106
	v_exp_f32_e32 v108, v83
	v_add_f32_e32 v106, v112, v106
	v_exp_f32_e32 v109, v84
	v_cvt_pk_bf16_f32 v104, v110, v111
	v_add_f32_e32 v106, v113, v106
	v_exp_f32_e32 v110, v85
	v_exp_f32_e32 v111, v86
	v_exp_f32_e32 v120, v97
	v_add_f32_e32 v97, v107, v106
	v_cvt_pk_bf16_f32 v105, v112, v113
	v_exp_f32_e32 v112, v87
	v_add_f32_e32 v97, v108, v97
	v_exp_f32_e32 v113, v88
	v_add_f32_e32 v97, v109, v97
	v_exp_f32_e32 v119, v89
	v_add_f32_e32 v97, v110, v97
	v_exp_f32_e32 v90, v90
	v_exp_f32_e32 v91, v91
	v_add_f32_e32 v97, v111, v97
	v_add_f32_e32 v97, v112, v97
	v_exp_f32_e32 v92, v92
	v_add_f32_e32 v97, v113, v97
	v_exp_f32_e32 v93, v93
	v_add_f32_e32 v97, v119, v97
	v_exp_f32_e32 v94, v94
	v_cvt_pk_bf16_f32 v86, v90, v91
	v_add_f32_e32 v90, v90, v97
	v_exp_f32_e32 v95, v95
	v_add_f32_e32 v90, v91, v90
	v_exp_f32_e32 v96, v96
	v_add_f32_e32 v90, v92, v90
	v_add_f32_e32 v90, v93, v90
	v_add_f32_e32 v90, v94, v90
	v_add_f32_e32 v90, v95, v90
	v_cvt_pk_bf16_f32 v99, v121, v122
	v_cvt_pk_bf16_f32 v100, v123, v124
	v_cvt_pk_bf16_f32 v101, v125, v126
	v_cvt_pk_bf16_f32 v82, v107, v108
	v_cvt_pk_bf16_f32 v83, v109, v110
	v_cvt_pk_bf16_f32 v84, v111, v112
	v_cvt_pk_bf16_f32 v85, v113, v119
	v_cvt_pk_bf16_f32 v87, v92, v93
	v_cvt_pk_bf16_f32 v88, v94, v95
	v_cvt_pk_bf16_f32 v89, v96, v120
	v_add_f32_e32 v119, v96, v90
	ds_read_b128 v[90:93], v16 offset:20480
	ds_read_b128 v[94:97], v17 offset:20480
	ds_read_b128 v[106:109], v118 offset:20480
	ds_read_b128 v[110:113], v2 offset:20480
	s_waitcnt lgkmcnt(0)
	v_mfma_f32_32x32x16_bf16 v[66:81], v[4:7], v[98:101], v[66:81]
	v_mfma_f32_32x32x16_bf16 v[66:81], v[8:11], v[102:105], v[66:81]
	v_mfma_f32_32x32x16_bf16 v[66:81], v[12:15], v[82:85], v[66:81]
	v_mfma_f32_32x32x16_bf16 v[66:81], v[114:117], v[86:89], v[66:81]
	ds_read_b128 v[4:7], v16 offset:24576
	ds_read_b128 v[8:11], v17 offset:24576
	ds_read_b128 v[12:15], v118 offset:24576
	ds_read_b128 v[114:117], v2 offset:24576
	v_mfma_f32_32x32x16_bf16 v[50:65], v[90:93], v[98:101], v[50:65]
	v_mfma_f32_32x32x16_bf16 v[50:65], v[94:97], v[102:105], v[50:65]
	v_mfma_f32_32x32x16_bf16 v[50:65], v[106:109], v[82:85], v[50:65]
	v_mfma_f32_32x32x16_bf16 v[50:65], v[110:113], v[86:89], v[50:65]
	ds_read_b128 v[90:93], v16 offset:28672
	ds_read_b128 v[94:97], v17 offset:28672
	ds_read_b128 v[106:109], v118 offset:28672
	ds_read_b128 v[110:113], v2 offset:28672
	s_waitcnt lgkmcnt(0)
	v_mfma_f32_32x32x16_bf16 v[34:49], v[4:7], v[98:101], v[34:49]
	v_mfma_f32_32x32x16_bf16 v[34:49], v[8:11], v[102:105], v[34:49]
	v_mfma_f32_32x32x16_bf16 v[34:49], v[12:15], v[82:85], v[34:49]
	v_mfma_f32_32x32x16_bf16 v[34:49], v[114:117], v[86:89], v[34:49]
	v_mfma_f32_32x32x16_bf16 v[18:33], v[90:93], v[98:101], v[18:33]
	v_add_f32_e32 v147, v120, v119
	v_mfma_f32_32x32x16_bf16 v[18:33], v[94:97], v[102:105], v[18:33]
	v_mfma_f32_32x32x16_bf16 v[18:33], v[106:109], v[82:85], v[18:33]
	v_mfma_f32_32x32x16_bf16 v[18:33], v[110:113], v[86:89], v[18:33]

; __global__ void __launch_bounds__(NT) mega(P p, int lo, int hi) {
;   extern __shared__ __attribute__((aligned(16))) char smem[];
	.amdhsa_kernel _Z4mega1Pii
		.amdhsa_group_segment_fixed_size 0
		.amdhsa_private_segment_fixed_size 0
		.amdhsa_kernarg_size 480
		.amdhsa_user_sgpr_count 2
		.amdhsa_user_sgpr_dispatch_ptr 0
		.amdhsa_user_sgpr_queue_ptr 0
		.amdhsa_user_sgpr_kernarg_segment_ptr 1
		.amdhsa_user_sgpr_dispatch_id 0
		.amdhsa_user_sgpr_kernarg_preload_length 0
		.amdhsa_user_sgpr_kernarg_preload_offset 0
		.amdhsa_user_sgpr_private_segment_size 0
		.amdhsa_uses_dynamic_stack 0
		.amdhsa_enable_private_segment 0
		.amdhsa_system_sgpr_workgroup_id_x 1
		.amdhsa_system_sgpr_workgroup_id_y 0
		.amdhsa_system_sgpr_workgroup_id_z 0
		.amdhsa_system_sgpr_workgroup_info 0
		.amdhsa_system_vgpr_workitem_id 2
		.amdhsa_next_free_vgpr 255
		.amdhsa_next_free_sgpr 102
		.amdhsa_accum_offset 256
		.amdhsa_reserve_vcc 1
		.amdhsa_float_round_mode_32 0
		.amdhsa_float_round_mode_16_64 0
		.amdhsa_float_denorm_mode_32 3
		.amdhsa_float_denorm_mode_16_64 3
		.amdhsa_dx10_clamp 1
		.amdhsa_ieee_mode 1
		.amdhsa_fp16_overflow 0
		.amdhsa_tg_split 0
		.amdhsa_exception_fp_ieee_invalid_op 0
		.amdhsa_exception_fp_denorm_src 0
		.amdhsa_exception_fp_ieee_div_zero 0
		.amdhsa_exception_fp_ieee_overflow 0
		.amdhsa_exception_fp_ieee_underflow 0
		.amdhsa_exception_fp_ieee_inexact 0
		.amdhsa_exception_int_div_zero 0
	.end_amdhsa_kernel

; __global__ void __launch_bounds__(NT) mega(P p, int lo, int hi) {
;   extern __shared__ __attribute__((aligned(16))) char smem[];
amdhsa.kernels:
  - .agpr_count:     0
    .args:
      - .offset:         0
        .size:           216
        .value_kind:     by_value
      - .offset:         216
        .size:           4
        .value_kind:     by_value
      - .offset:         220
        .size:           4
        .value_kind:     by_value
      - .offset:         224
        .size:           4
        .value_kind:     hidden_block_count_x
      - .offset:         228
        .size:           4
        .value_kind:     hidden_block_count_y
      - .offset:         232
        .size:           4
        .value_kind:     hidden_block_count_z
      - .offset:         236
        .size:           2
        .value_kind:     hidden_group_size_x
      - .offset:         238
        .size:           2
        .value_kind:     hidden_group_size_y
      - .offset:         240
        .size:           2
        .value_kind:     hidden_group_size_z
      - .offset:         242
        .size:           2
        .value_kind:     hidden_remainder_x
      - .offset:         244
        .size:           2
        .value_kind:     hidden_remainder_y
      - .offset:         246
        .size:           2
        .value_kind:     hidden_remainder_z
      - .offset:         264
        .size:           8
        .value_kind:     hidden_global_offset_x
      - .offset:         272
        .size:           8
        .value_kind:     hidden_global_offset_y
      - .offset:         280
        .size:           8
        .value_kind:     hidden_global_offset_z
      - .offset:         288
        .size:           2
        .value_kind:     hidden_grid_dims
      - .offset:         312
        .size:           8
        .value_kind:     hidden_multigrid_sync_arg
      - .offset:         344
        .size:           4
        .value_kind:     hidden_dynamic_lds_size
    .group_segment_fixed_size: 0
    .kernarg_segment_align: 8
    .kernarg_segment_size: 480
    .language:       OpenCL C
    .language_version:
      - 2
      - 0
    .max_flat_workgroup_size: 512
    .name:           _Z4mega1Pii
    .private_segment_fixed_size: 0
    .sgpr_count:     108
    .sgpr_spill_count: 313
    .symbol:         _Z4mega1Pii.kd
    .uniform_work_group_size: 1
    .uses_dynamic_stack: false
    .vgpr_count:     255
    .vgpr_spill_count: 0
    .wavefront_size: 64
